# speedup vs baseline: 1.0071x; 1.0004x over previous
; __device__ __forceinline__ void attn_phase(const u16* __restrict__ QK, const u16* __restrict__ Vt, u16* __restrict__ AO, const int wave) {
;     ...
;       const int k0 = kt * 32;
;       f32x16 s;
;       _Pragma("unroll") for (int r = 0; r < 16; ++r) s[r] = 0.f;
;       _Pragma("unroll") for (int kk = 0; kk < 8; ++kk) s = __builtin_amdgcn_mfma_f32_32x32x16_bf16(kf[kk], qf[kk], s, 0, 0, 0);
;       __builtin_amdgcn_sched_barrier(0);
;       {
;         const int kn = (kt > 0 ? kt - 1 : 0) * 32;
;         _Pragma("unroll") for (int kk = 0; kk < 8; ++kk) kf[kk] = *reinterpret_cast<const bf16x8*>(kbase + (long)kn * QK_LD + kk * 16);
;       }
;       u32x4 vfr[2][4];
;       _Pragma("unroll") for (int t = 0; t < 2; ++t) _Pragma("unroll") for (int dt = 0; dt < 4; ++dt)
;         vfr[t][dt] = *reinterpret_cast<const u32x4*>(vbase + (long)dt * 32 * VT_LD + k0 + 8 * t);
;       __builtin_amdgcn_sched_barrier(0);
;       float lk[16], w[16];
;       float tot = 0.f;
;       _Pragma("unroll") for (int r = 15; r >= 0; --r) {
;         const float z = s[r] * SB_SCALE;
;         s[r] = z;
;         const float sp = fmaxf(z, 0.f) + __logf(1.0f + __expf(-fabsf(z)));
;         tot += (k0 + 16 * hh + r < qpos) ? -sp : 0.f;
;         lk[r] = tot;
.LBB0_256:
	s_waitcnt vmcnt(0)
	v_mfma_f32_32x32x16_bf16 v[64:79], v[140:143], v[80:83], 0
	v_mfma_f32_32x32x16_bf16 v[64:79], v[136:139], v[84:87], v[64:79]
	v_mfma_f32_32x32x16_bf16 v[64:79], v[132:135], v[88:91], v[64:79]
	v_mfma_f32_32x32x16_bf16 v[64:79], v[128:131], v[92:95], v[64:79]
	v_mfma_f32_32x32x16_bf16 v[64:79], v[124:127], v[96:99], v[64:79]
	v_mfma_f32_32x32x16_bf16 v[64:79], v[120:123], v[100:103], v[64:79]
	v_mfma_f32_32x32x16_bf16 v[64:79], v[116:119], v[104:107], v[64:79]
	v_min_u32_e32 v116, 1, v187
	v_mfma_f32_32x32x16_bf16 v[64:79], v[112:115], v[108:111], v[64:79]
	v_lshlrev_b32_e32 v112, 5, v116
	v_sub_u32_e32 v112, v178, v112
	v_mad_u64_u32 v[112:113], s[4:5], v112, s3, v[192:193]
	v_lshl_add_u64 v[144:145], v[178:179], 1, v[194:195]
	v_add_co_u32_e64 v148, s[4:5], s40, v144
	global_load_dwordx4 v[140:143], v[112:113], off offset:2048
	global_load_dwordx4 v[136:139], v[112:113], off offset:2080
	global_load_dwordx4 v[132:135], v[112:113], off offset:2112
	global_load_dwordx4 v[128:131], v[112:113], off offset:2144
	global_load_dwordx4 v[124:127], v[112:113], off offset:2176
	global_load_dwordx4 v[120:123], v[112:113], off offset:2208
	global_load_dwordx4 v[116:119], v[112:113], off offset:2240
	s_nop 0
	global_load_dwordx4 v[112:115], v[112:113], off offset:2272
	v_addc_co_u32_e64 v149, s[4:5], 0, v145, s[4:5]
	v_add_co_u32_e64 v152, s[4:5], s41, v144
	s_nop 1
	v_addc_co_u32_e64 v153, s[4:5], 0, v145, s[4:5]
	v_add_co_u32_e64 v156, s[4:5], s46, v144
	s_nop 1
	v_addc_co_u32_e64 v157, s[4:5], 0, v145, s[4:5]
	global_load_dwordx4 v[172:175], v[144:145], off
	s_nop 0
	global_load_dwordx4 v[144:147], v[144:145], off offset:16
	s_nop 0
	global_load_dwordx4 v[168:171], v[148:149], off
	s_nop 0
	global_load_dwordx4 v[148:151], v[148:149], off offset:16
	s_nop 0
	global_load_dwordx4 v[164:167], v[152:153], off
	s_nop 0
	global_load_dwordx4 v[152:155], v[152:153], off offset:16
	s_nop 0
	global_load_dwordx4 v[160:163], v[156:157], off
	s_nop 0
	global_load_dwordx4 v[156:159], v[156:157], off offset:16
	v_mul_f32_e32 v202, 0x3db504f3, v79
	v_max_f32_e32 v203, 0, v202
	v_mul_f32_e64 v202, |v202|, s47
	v_exp_f32_e32 v202, v202
	v_add_u32_e32 v208, v181, v178
	v_add_u32_e32 v187, -1, v187
	v_subrev_u32_e32 v178, 32, v178
	v_add_f32_e32 v202, 1.0, v202
	v_log_f32_e32 v202, v202
	s_nop 0
	v_mul_f32_e32 v204, 0x3f317217, v202
	v_fma_f32 v204, v202, s51, -v204
	v_fmac_f32_e32 v204, 0x3377d1cf, v202
	v_fmac_f32_e32 v204, 0x3f317217, v202
	v_add_f32_e32 v202, v203, v204
	v_add_u32_e32 v203, 15, v208
	v_cmp_lt_i32_e64 s[4:5], v203, v185
	v_mul_f32_e32 v203, 0x3db504f3, v78
	v_max_f32_e32 v204, 0, v203
	v_mul_f32_e64 v203, |v203|, s47
	v_exp_f32_e32 v203, v203
	v_sub_f32_e32 v202, 0, v202
	v_cndmask_b32_e64 v202, 0, v202, s[4:5]
	v_add_f32_e32 v203, 1.0, v203
	v_log_f32_e32 v203, v203
	s_nop 0
	v_mul_f32_e32 v205, 0x3f317217, v203
	v_fma_f32 v205, v203, s51, -v205
	v_fmac_f32_e32 v205, 0x3377d1cf, v203
	v_fmac_f32_e32 v205, 0x3f317217, v203
	v_add_f32_e32 v203, v204, v205
	v_add_u32_e32 v204, 14, v208
	v_cmp_lt_i32_e64 s[6:7], v204, v185
	v_mul_f32_e32 v204, 0x3db504f3, v77
	v_max_f32_e32 v205, 0, v204
	v_mul_f32_e64 v204, |v204|, s47
	v_exp_f32_e32 v204, v204
	v_cndmask_b32_e64 v203, 0, -v203, s[6:7]
	v_add_f32_e32 v203, v203, v202
	v_add_f32_e32 v204, 1.0, v204
	v_log_f32_e32 v204, v204
	s_nop 0
	v_mul_f32_e32 v206, 0x3f317217, v204
	v_fma_f32 v206, v204, s51, -v206
	v_fmac_f32_e32 v206, 0x3377d1cf, v204
	v_fmac_f32_e32 v206, 0x3f317217, v204
	v_add_f32_e32 v204, v205, v206
	v_add_u32_e32 v205, 13, v208
	v_cmp_lt_i32_e64 s[8:9], v205, v185
	v_mul_f32_e32 v205, 0x3db504f3, v76
	v_max_f32_e32 v206, 0, v205
	v_mul_f32_e64 v205, |v205|, s47
	v_exp_f32_e32 v205, v205
	v_cndmask_b32_e64 v204, 0, -v204, s[8:9]
	v_add_f32_e32 v204, v204, v203
	v_add_f32_e32 v205, 1.0, v205
	v_log_f32_e32 v205, v205
	s_nop 0
	v_mul_f32_e32 v207, 0x3f317217, v205
	v_fma_f32 v207, v205, s51, -v207
	v_fmac_f32_e32 v207, 0x3377d1cf, v205
	v_fmac_f32_e32 v207, 0x3f317217, v205
	v_add_f32_e32 v205, v206, v207
	v_add_u32_e32 v206, 12, v208
	v_cmp_lt_i32_e64 s[10:11], v206, v185
	v_mul_f32_e32 v206, 0x3db504f3, v75
	v_max_f32_e32 v207, 0, v206
	v_mul_f32_e64 v206, |v206|, s47
	v_exp_f32_e32 v206, v206
	v_cndmask_b32_e64 v205, 0, -v205, s[10:11]
	v_add_f32_e32 v205, v205, v204
	v_add_f32_e32 v206, 1.0, v206
	v_log_f32_e32 v206, v206
	s_nop 0
	v_mul_f32_e32 v209, 0x3f317217, v206
	v_fma_f32 v209, v206, s51, -v209
	v_fmac_f32_e32 v209, 0x3377d1cf, v206
	v_fmac_f32_e32 v209, 0x3f317217, v206
	v_add_f32_e32 v206, v207, v209
	v_add_u32_e32 v207, 11, v208
	v_cmp_lt_i32_e64 s[12:13], v207, v185
	v_mul_f32_e32 v207, 0x3db504f3, v74
	v_max_f32_e32 v209, 0, v207
	v_mul_f32_e64 v207, |v207|, s47
	v_exp_f32_e32 v207, v207
	v_cndmask_b32_e64 v206, 0, -v206, s[12:13]
	v_add_f32_e32 v206, v206, v205
	v_add_f32_e32 v207, 1.0, v207
	v_log_f32_e32 v207, v207
	s_nop 0
	v_mul_f32_e32 v210, 0x3f317217, v207
	v_fma_f32 v210, v207, s51, -v210
	v_fmac_f32_e32 v210, 0x3377d1cf, v207
	v_fmac_f32_e32 v210, 0x3f317217, v207
	v_add_f32_e32 v207, v209, v210
	v_add_u32_e32 v209, 10, v208
	v_cmp_lt_i32_e64 s[14:15], v209, v185
	v_mul_f32_e32 v209, 0x3db504f3, v73
	v_max_f32_e32 v210, 0, v209
	v_mul_f32_e64 v209, |v209|, s47
	v_exp_f32_e32 v209, v209
	v_cndmask_b32_e64 v207, 0, -v207, s[14:15]
	v_add_f32_e32 v207, v207, v206
	v_add_f32_e32 v209, 1.0, v209
	v_log_f32_e32 v209, v209
	s_nop 0
	v_mul_f32_e32 v211, 0x3f317217, v209
	v_fma_f32 v211, v209, s51, -v211
	v_fmac_f32_e32 v211, 0x3377d1cf, v209
	v_fmac_f32_e32 v211, 0x3f317217, v209
	v_add_f32_e32 v209, v210, v211
	v_add_u32_e32 v210, 9, v208
; __device__ __forceinline__ void attn_phase(const u16* __restrict__ QK, const u16* __restrict__ Vt, u16* __restrict__ AO, const int wave) {
;     ...
;       _Pragma("unroll") for (int r = 15; r >= 0; --r) {
;         const float z = s[r] * SB_SCALE;
;         s[r] = z;
;         const float sp = fmaxf(z, 0.f) + __logf(1.0f + __expf(-fabsf(z)));
;         tot += (k0 + 16 * hh + r < qpos) ? -sp : 0.f;
;         lk[r] = tot;
;       }
;       const float ptot = __shfl_xor(tot, 32);
	v_cmp_lt_i32_e64 s[16:17], v210, v185
	v_mul_f32_e32 v210, 0x3db504f3, v72
	v_max_f32_e32 v211, 0, v210
	v_mul_f32_e64 v210, |v210|, s47
	v_exp_f32_e32 v210, v210
	v_cndmask_b32_e64 v209, 0, -v209, s[16:17]
	v_add_f32_e32 v209, v209, v207
	v_add_f32_e32 v210, 1.0, v210
	v_log_f32_e32 v210, v210
	s_nop 0
	v_mul_f32_e32 v212, 0x3f317217, v210
	v_fma_f32 v212, v210, s51, -v212
	v_fmac_f32_e32 v212, 0x3377d1cf, v210
	v_fmac_f32_e32 v212, 0x3f317217, v210
	v_add_f32_e32 v210, v211, v212
	v_add_u32_e32 v211, 8, v208
	v_cmp_lt_i32_e64 s[18:19], v211, v185
	v_mul_f32_e32 v211, 0x3db504f3, v71
	v_max_f32_e32 v212, 0, v211
	v_mul_f32_e64 v211, |v211|, s47
	v_exp_f32_e32 v211, v211
	v_cndmask_b32_e64 v210, 0, -v210, s[18:19]
	v_add_f32_e32 v210, v210, v209
	v_add_f32_e32 v211, 1.0, v211
	v_log_f32_e32 v211, v211
	s_nop 0
	v_mul_f32_e32 v213, 0x3f317217, v211
	v_fma_f32 v213, v211, s51, -v213
	v_fmac_f32_e32 v213, 0x3377d1cf, v211
	v_fmac_f32_e32 v213, 0x3f317217, v211
	v_add_f32_e32 v211, v212, v213
	v_add_u32_e32 v212, 7, v208
	v_cmp_lt_i32_e64 s[20:21], v212, v185
	v_mul_f32_e32 v212, 0x3db504f3, v70
	v_max_f32_e32 v213, 0, v212
	v_mul_f32_e64 v212, |v212|, s47
	v_exp_f32_e32 v212, v212
	v_cndmask_b32_e64 v211, 0, -v211, s[20:21]
	v_add_f32_e32 v211, v211, v210
	v_add_f32_e32 v212, 1.0, v212
	v_log_f32_e32 v212, v212
	s_nop 0
	v_mul_f32_e32 v214, 0x3f317217, v212
	v_fma_f32 v214, v212, s51, -v214
	v_fmac_f32_e32 v214, 0x3377d1cf, v212
	v_fmac_f32_e32 v214, 0x3f317217, v212
	v_add_f32_e32 v212, v213, v214
	v_add_u32_e32 v213, 6, v208
	v_cmp_lt_i32_e64 s[22:23], v213, v185
	v_mul_f32_e32 v213, 0x3db504f3, v69
	v_max_f32_e32 v214, 0, v213
	v_mul_f32_e64 v213, |v213|, s47
	v_exp_f32_e32 v213, v213
	v_cndmask_b32_e64 v212, 0, -v212, s[22:23]
	v_add_f32_e32 v212, v212, v211
	v_add_f32_e32 v213, 1.0, v213
	v_log_f32_e32 v213, v213
	s_nop 0
	v_mul_f32_e32 v215, 0x3f317217, v213
	v_fma_f32 v215, v213, s51, -v215
	v_fmac_f32_e32 v215, 0x3377d1cf, v213
	v_fmac_f32_e32 v215, 0x3f317217, v213
	v_add_f32_e32 v213, v214, v215
	v_add_u32_e32 v214, 5, v208
	v_cmp_lt_i32_e64 s[24:25], v214, v185
	v_mul_f32_e32 v214, 0x3db504f3, v68
	v_max_f32_e32 v215, 0, v214
	v_mul_f32_e64 v214, |v214|, s47
	v_exp_f32_e32 v214, v214
	v_cndmask_b32_e64 v213, 0, -v213, s[24:25]
	v_add_f32_e32 v213, v213, v212
	v_add_f32_e32 v214, 1.0, v214
	v_log_f32_e32 v214, v214
	s_nop 0
	v_mul_f32_e32 v216, 0x3f317217, v214
	v_fma_f32 v216, v214, s51, -v216
	v_fmac_f32_e32 v216, 0x3377d1cf, v214
	v_fmac_f32_e32 v216, 0x3f317217, v214
	v_add_f32_e32 v214, v215, v216
	v_add_u32_e32 v215, 4, v208
	v_cmp_lt_i32_e64 s[26:27], v215, v185
	v_mul_f32_e32 v215, 0x3db504f3, v67
	v_max_f32_e32 v216, 0, v215
	v_mul_f32_e64 v215, |v215|, s47
	v_exp_f32_e32 v215, v215
	v_cndmask_b32_e64 v214, 0, -v214, s[26:27]
	v_add_f32_e32 v214, v214, v213
	v_add_f32_e32 v215, 1.0, v215
	v_log_f32_e32 v215, v215
	s_nop 0
	v_mul_f32_e32 v217, 0x3f317217, v215
	v_fma_f32 v217, v215, s51, -v217
	v_fmac_f32_e32 v217, 0x3377d1cf, v215
	v_fmac_f32_e32 v217, 0x3f317217, v215
	v_add_f32_e32 v215, v216, v217
	v_add_u32_e32 v216, 3, v208
	v_cmp_lt_i32_e64 s[28:29], v216, v185
	v_mul_f32_e32 v216, 0x3db504f3, v66
	v_max_f32_e32 v217, 0, v216
	v_mul_f32_e64 v216, |v216|, s47
	v_exp_f32_e32 v216, v216
	v_cndmask_b32_e64 v215, 0, -v215, s[28:29]
	v_add_f32_e32 v215, v215, v214
	v_add_f32_e32 v216, 1.0, v216
	v_log_f32_e32 v216, v216
	s_nop 0
	v_mul_f32_e32 v218, 0x3f317217, v216
	v_fma_f32 v218, v216, s51, -v218
	v_fmac_f32_e32 v218, 0x3377d1cf, v216
	v_fmac_f32_e32 v218, 0x3f317217, v216
	v_add_f32_e32 v216, v217, v218
	v_add_u32_e32 v217, 2, v208
	v_cmp_lt_i32_e64 s[30:31], v217, v185
	v_mul_f32_e32 v217, 0x3db504f3, v65
	v_max_f32_e32 v218, 0, v217
	v_mul_f32_e64 v217, |v217|, s47
	v_exp_f32_e32 v217, v217
	v_cndmask_b32_e64 v216, 0, -v216, s[30:31]
	v_add_f32_e32 v216, v216, v215
	v_add_f32_e32 v217, 1.0, v217
	v_log_f32_e32 v217, v217
	s_nop 0
	v_mul_f32_e32 v219, 0x3f317217, v217
	v_fma_f32 v219, v217, s51, -v219
	v_fmac_f32_e32 v219, 0x3377d1cf, v217
	v_fmac_f32_e32 v219, 0x3f317217, v217
	v_add_f32_e32 v217, v218, v219
	v_add_u32_e32 v218, 1, v208
	v_cmp_lt_i32_e64 s[34:35], v218, v185
	v_mul_f32_e32 v218, 0x3db504f3, v64
	v_max_f32_e32 v219, 0, v218
	v_mul_f32_e64 v218, |v218|, s47
	v_exp_f32_e32 v218, v218
	v_cndmask_b32_e64 v217, 0, -v217, s[34:35]
	v_add_f32_e32 v217, v217, v216
	v_add_f32_e32 v218, 1.0, v218
	v_log_f32_e32 v218, v218
	s_nop 0
	v_mul_f32_e32 v220, 0x3f317217, v218
	v_fma_f32 v220, v218, s51, -v220
	v_fmac_f32_e32 v220, 0x3377d1cf, v218
	v_fmac_f32_e32 v220, 0x3f317217, v218
	v_add_f32_e32 v218, v219, v220
	v_cmp_lt_i32_e64 s[36:37], v208, v185
	s_nop 1
	v_cndmask_b32_e64 v208, 0, -v218, s[36:37]
	v_add_f32_e32 v208, v208, v217
	ds_bpermute_b32 v218, v191, v208
	s_waitcnt lgkmcnt(0)
; __device__ __forceinline__ void attn_phase(const u16* __restrict__ QK, const u16* __restrict__ Vt, u16* __restrict__ AO, const int wave) {
;     ...
;       _Pragma("unroll") for (int r = 0; r < 16; ++r) {
;         const float lw = s[r] + base + lk[r];
;         const float wv = __expf(fminf(lw, 0.f));
;         w[r] = (k0 + 16 * hh + r < qpos) ? wv : 0.f;
;       }
;       carry += tot + ptot;
;       _Pragma("unroll") for (int t = 0; t < 2; ++t) {
;         u32x4 u;
;         u[0] = pack2(w[8 * t + 0], w[8 * t + 1]); u[1] = pack2(w[8 * t + 2], w[8 * t + 3]);
;         u[2] = pack2(w[8 * t + 4], w[8 * t + 5]); u[3] = pack2(w[8 * t + 6], w[8 * t + 7]);
;         const bf16x8 pb = *reinterpret_cast<bf16x8*>(&u);
;         _Pragma("unroll") for (int dt = 0; dt < 4; ++dt) {
;           const bf16x8 va = *reinterpret_cast<bf16x8*>(&vfr[t][dt]);
;           o[dt] = __builtin_amdgcn_mfma_f32_32x32x16_bf16(va, pb, o[dt], 0, 0, 0);
;         }
;       }
;       if (__all(carry < -104.0f)) break;
	v_cndmask_b32_e32 v219, 0, v218, vcc
	v_add_f32_e32 v219, v201, v219
	v_fmamk_f32 v64, v64, 0x3db504f3, v219
	v_fmamk_f32 v65, v65, 0x3db504f3, v219
	v_fmamk_f32 v66, v66, 0x3db504f3, v219
	v_fmamk_f32 v67, v67, 0x3db504f3, v219
	v_add_f32_e32 v64, v64, v208
	v_add_f32_e32 v65, v65, v217
	v_add_f32_e32 v66, v66, v216
	v_add_f32_e32 v67, v215, v67
	v_fmamk_f32 v68, v68, 0x3db504f3, v219
	v_fmamk_f32 v69, v69, 0x3db504f3, v219
	v_fmamk_f32 v70, v70, 0x3db504f3, v219
	v_fmamk_f32 v71, v71, 0x3db504f3, v219
	v_min_f32_e32 v64, 0, v64
	v_min_f32_e32 v65, 0, v65
	v_min_f32_e32 v66, 0, v66
	v_min_f32_e32 v67, 0, v67
	v_add_f32_e32 v68, v214, v68
	v_add_f32_e32 v69, v213, v69
	v_add_f32_e32 v70, v212, v70
	v_add_f32_e32 v71, v211, v71
	v_mul_f32_e32 v64, 0x3fb8aa3b, v64
	v_mul_f32_e32 v65, 0x3fb8aa3b, v65
	v_mul_f32_e32 v66, 0x3fb8aa3b, v66
	v_mul_f32_e32 v67, 0x3fb8aa3b, v67
	v_min_f32_e32 v68, 0, v68
	v_min_f32_e32 v69, 0, v69
	v_min_f32_e32 v70, 0, v70
	v_min_f32_e32 v71, 0, v71
	v_exp_f32_e32 v64, v64
	v_exp_f32_e32 v65, v65
	v_exp_f32_e32 v66, v66
	v_exp_f32_e32 v67, v67
	v_mul_f32_e32 v68, 0x3fb8aa3b, v68
	v_mul_f32_e32 v69, 0x3fb8aa3b, v69
	v_mul_f32_e32 v70, 0x3fb8aa3b, v70
	v_mul_f32_e32 v71, 0x3fb8aa3b, v71
	v_exp_f32_e32 v68, v68
	v_exp_f32_e32 v69, v69
	v_exp_f32_e32 v70, v70
	v_exp_f32_e32 v71, v71
	v_cndmask_b32_e64 v64, 0, v64, s[36:37]
	v_cndmask_b32_e64 v65, 0, v65, s[34:35]
	v_cndmask_b32_e64 v66, 0, v66, s[30:31]
	v_cndmask_b32_e64 v67, 0, v67, s[28:29]
	v_cndmask_b32_e64 v68, 0, v68, s[26:27]
	v_cndmask_b32_e64 v69, 0, v69, s[24:25]
	v_cndmask_b32_e64 v70, 0, v70, s[22:23]
	v_cndmask_b32_e64 v71, 0, v71, s[20:21]
	v_fmamk_f32 v72, v72, 0x3db504f3, v219
	v_fmamk_f32 v73, v73, 0x3db504f3, v219
	v_fmamk_f32 v74, v74, 0x3db504f3, v219
	v_fmamk_f32 v75, v75, 0x3db504f3, v219
	v_fmamk_f32 v76, v76, 0x3db504f3, v219
	v_fmamk_f32 v77, v77, 0x3db504f3, v219
	v_fmamk_f32 v78, v78, 0x3db504f3, v219
	v_fmac_f32_e32 v219, 0x3db504f3, v79
	v_cvt_pk_bf16_f32 v64, v64, v65
	v_cvt_pk_bf16_f32 v65, v66, v67
	v_cvt_pk_bf16_f32 v66, v68, v69
	v_cvt_pk_bf16_f32 v67, v70, v71
	v_add_f32_e32 v72, v210, v72
	s_waitcnt vmcnt(7)
	v_mfma_f32_32x32x16_bf16 v[48:63], v[172:175], v[64:67], v[48:63]
	v_add_f32_e32 v73, v209, v73
	v_add_f32_e32 v74, v207, v74
	v_add_f32_e32 v75, v206, v75
	v_add_f32_e32 v76, v205, v76
	v_add_f32_e32 v77, v204, v77
	v_add_f32_e32 v78, v203, v78
	v_add_f32_e32 v79, v202, v219
	s_waitcnt vmcnt(5)
	v_mfma_f32_32x32x16_bf16 v[32:47], v[168:171], v[64:67], v[32:47]
	v_min_f32_e32 v72, 0, v72
	v_min_f32_e32 v73, 0, v73
	v_min_f32_e32 v74, 0, v74
	v_min_f32_e32 v75, 0, v75
	v_min_f32_e32 v76, 0, v76
	v_min_f32_e32 v77, 0, v77
	v_min_f32_e32 v78, 0, v78
	s_waitcnt vmcnt(3)
	v_mfma_f32_32x32x16_bf16 v[16:31], v[164:167], v[64:67], v[16:31]
	v_min_f32_e32 v79, 0, v79
	v_mul_f32_e32 v72, 0x3fb8aa3b, v72
	v_mul_f32_e32 v73, 0x3fb8aa3b, v73
	v_mul_f32_e32 v74, 0x3fb8aa3b, v74
	v_mul_f32_e32 v75, 0x3fb8aa3b, v75
	v_mul_f32_e32 v76, 0x3fb8aa3b, v76
	v_mul_f32_e32 v77, 0x3fb8aa3b, v77
	s_waitcnt vmcnt(1)
	v_mfma_f32_32x32x16_bf16 v[0:15], v[160:163], v[64:67], v[0:15]
	v_mul_f32_e32 v78, 0x3fb8aa3b, v78
	v_mul_f32_e32 v79, 0x3fb8aa3b, v79
	v_exp_f32_e32 v72, v72
	v_exp_f32_e32 v73, v73
	v_exp_f32_e32 v74, v74
	v_exp_f32_e32 v75, v75
	v_exp_f32_e32 v76, v76
	v_exp_f32_e32 v77, v77
	v_exp_f32_e32 v78, v78
	v_exp_f32_e32 v79, v79
	v_cndmask_b32_e64 v72, 0, v72, s[18:19]
	v_cndmask_b32_e64 v73, 0, v73, s[16:17]
	v_cndmask_b32_e64 v74, 0, v74, s[14:15]
	v_cndmask_b32_e64 v75, 0, v75, s[12:13]
	v_cndmask_b32_e64 v76, 0, v76, s[10:11]
	v_cndmask_b32_e64 v77, 0, v77, s[8:9]
	v_cndmask_b32_e64 v78, 0, v78, s[6:7]
	v_cndmask_b32_e64 v79, 0, v79, s[4:5]
	v_add_f32_e32 v202, v208, v218
	v_cvt_pk_bf16_f32 v64, v72, v73
	v_cvt_pk_bf16_f32 v65, v74, v75
	v_cvt_pk_bf16_f32 v66, v76, v77
	v_cvt_pk_bf16_f32 v67, v78, v79
	v_add_f32_e32 v201, v201, v202
	v_mfma_f32_32x32x16_bf16 v[48:63], v[144:147], v[64:67], v[48:63]
	v_cmp_gt_f32_e64 s[4:5], s53, v201
	s_cmp_eq_u64 s[4:5], exec
	s_cselect_b64 s[6:7], -1, 0
	v_cmp_eq_u32_e64 s[4:5], 0, v200
	s_or_b64 s[4:5], s[4:5], s[6:7]
	s_and_b64 s[4:5], exec, s[4:5]
	v_add_u32_e32 v200, 1, v200
	v_mfma_f32_32x32x16_bf16 v[32:47], v[148:151], v[64:67], v[32:47]
	s_or_b64 s[60:61], s[4:5], s[60:61]
	v_mfma_f32_32x32x16_bf16 v[16:31], v[152:155], v[64:67], v[16:31]
	s_waitcnt vmcnt(0)
	v_mfma_f32_32x32x16_bf16 v[0:15], v[156:159], v[64:67], v[0:15]
	s_andn2_b64 exec, exec, s[60:61]
	s_cbranch_execnz .LBB0_256
	s_or_b64 exec, exec, s[60:61]
	s_branch .LBB0_253
